# hot loop headers (GEMM K-loops, attention loops) aligned to 64 bytes with s_nop fill
# baseline (speedup 1.0000x reference)
.LBB0_196:
	s_ashr_i32 s79, s78, 31
	s_lshl_b64 s[12:13], s[78:79], 19
	s_add_u32 s80, s19, s12
	s_addc_u32 s81, s66, s13
	s_and_b64 s[12:13], s[6:7], exec
	s_cselect_b32 s15, s81, s9
	s_cselect_b32 s23, s80, s8
	s_ashr_i32 s77, s76, 31
	s_lshl_b64 s[12:13], s[76:77], 19
	s_add_u32 s82, s67, s12
	s_addc_u32 s83, s88, s13
	s_and_b64 s[12:13], s[6:7], exec
	s_cselect_b32 s77, s83, s85
	s_cselect_b32 s79, s82, s84
	s_add_u32 s8, s8, 0x40080
	s_addc_u32 s9, s9, 0
	s_add_u32 vcc_lo, s84, 0x100
	v_mov_b32_e32 v2, 0
	s_addc_u32 vcc_hi, s85, 0
	s_mov_b32 s12, -2
	v_mov_b32_e32 v3, v2
	v_mov_b32_e32 v4, v2
	v_mov_b32_e32 v5, v2
	v_mov_b32_e32 v6, v2
	v_mov_b32_e32 v7, v2
	v_mov_b32_e32 v8, v2
	v_mov_b32_e32 v9, v2
	v_mov_b32_e32 v18, v2
	v_mov_b32_e32 v19, v2
	v_mov_b32_e32 v20, v2
	v_mov_b32_e32 v21, v2
	v_mov_b32_e32 v22, v2
	v_mov_b32_e32 v23, v2
	v_mov_b32_e32 v24, v2
	v_mov_b32_e32 v25, v2
	v_mov_b32_e32 v50, v2
	v_mov_b32_e32 v51, v2
	v_mov_b32_e32 v52, v2
	v_mov_b32_e32 v53, v2
	v_mov_b32_e32 v54, v2
	v_mov_b32_e32 v55, v2
	v_mov_b32_e32 v56, v2
	v_mov_b32_e32 v57, v2
	v_mov_b32_e32 v66, v2
	v_mov_b32_e32 v67, v2
	v_mov_b32_e32 v68, v2
	v_mov_b32_e32 v69, v2
	v_mov_b32_e32 v70, v2
	v_mov_b32_e32 v71, v2
	v_mov_b32_e32 v72, v2
	v_mov_b32_e32 v73, v2
	v_mov_b32_e32 v10, v2
	v_mov_b32_e32 v11, v2
	v_mov_b32_e32 v12, v2
	v_mov_b32_e32 v13, v2
	v_mov_b32_e32 v14, v2
	v_mov_b32_e32 v15, v2
	v_mov_b32_e32 v16, v2
	v_mov_b32_e32 v17, v2
	v_mov_b32_e32 v26, v2
	v_mov_b32_e32 v27, v2
	v_mov_b32_e32 v28, v2
	v_mov_b32_e32 v29, v2
	v_mov_b32_e32 v30, v2
	v_mov_b32_e32 v31, v2
	v_mov_b32_e32 v32, v2
	v_mov_b32_e32 v33, v2
	v_mov_b32_e32 v58, v2
	v_mov_b32_e32 v59, v2
	v_mov_b32_e32 v60, v2
	v_mov_b32_e32 v61, v2
	v_mov_b32_e32 v62, v2
	v_mov_b32_e32 v63, v2
	v_mov_b32_e32 v64, v2
	v_mov_b32_e32 v65, v2
	v_mov_b32_e32 v74, v2
	v_mov_b32_e32 v75, v2
	v_mov_b32_e32 v76, v2
	v_mov_b32_e32 v77, v2
	v_mov_b32_e32 v78, v2
	v_mov_b32_e32 v79, v2
	v_mov_b32_e32 v80, v2
	v_mov_b32_e32 v81, v2
	v_mov_b32_e32 v82, v2
	v_mov_b32_e32 v83, v2
	v_mov_b32_e32 v84, v2
	v_mov_b32_e32 v85, v2
	v_mov_b32_e32 v86, v2
	v_mov_b32_e32 v87, v2
	v_mov_b32_e32 v88, v2
	v_mov_b32_e32 v89, v2
	v_mov_b32_e32 v98, v2
	v_mov_b32_e32 v99, v2
	v_mov_b32_e32 v100, v2
	v_mov_b32_e32 v101, v2
	v_mov_b32_e32 v102, v2
	v_mov_b32_e32 v103, v2
	v_mov_b32_e32 v104, v2
	v_mov_b32_e32 v105, v2
	v_mov_b32_e32 v114, v2
	v_mov_b32_e32 v115, v2
	v_mov_b32_e32 v116, v2
	v_mov_b32_e32 v117, v2
	v_mov_b32_e32 v118, v2
	v_mov_b32_e32 v119, v2
	v_mov_b32_e32 v120, v2
	v_mov_b32_e32 v121, v2
	v_mov_b32_e32 v130, v2
	v_mov_b32_e32 v131, v2
	v_mov_b32_e32 v132, v2
	v_mov_b32_e32 v133, v2
	v_mov_b32_e32 v134, v2
	v_mov_b32_e32 v135, v2
	v_mov_b32_e32 v136, v2
	v_mov_b32_e32 v137, v2
	v_mov_b32_e32 v90, v2
	v_mov_b32_e32 v91, v2
	v_mov_b32_e32 v92, v2
	v_mov_b32_e32 v93, v2
	v_mov_b32_e32 v94, v2
	v_mov_b32_e32 v95, v2
	v_mov_b32_e32 v96, v2
	v_mov_b32_e32 v97, v2
	v_mov_b32_e32 v106, v2
	v_mov_b32_e32 v107, v2
	v_mov_b32_e32 v108, v2
	v_mov_b32_e32 v109, v2
	v_mov_b32_e32 v110, v2
	v_mov_b32_e32 v111, v2
	v_mov_b32_e32 v112, v2
	v_mov_b32_e32 v113, v2
	v_mov_b32_e32 v122, v2
	v_mov_b32_e32 v123, v2
	v_mov_b32_e32 v124, v2
	v_mov_b32_e32 v125, v2
	v_mov_b32_e32 v126, v2
	v_mov_b32_e32 v127, v2
	v_mov_b32_e32 v128, v2
	v_mov_b32_e32 v129, v2
	v_mov_b32_e32 v138, v2
	v_mov_b32_e32 v139, v2
	v_mov_b32_e32 v140, v2
	v_mov_b32_e32 v141, v2
	v_mov_b32_e32 v142, v2
	v_mov_b32_e32 v143, v2
	v_mov_b32_e32 v144, v2
	v_mov_b32_e32 v145, v2
	.p2alignl 6, 3212836864

.LBB0_496:
	s_lshl_b64 s[12:13], s[70:71], 1
	s_add_u32 s3, s23, s12
	s_addc_u32 s8, s27, s13
	s_lshl_b64 s[12:13], s[74:75], 1
	v_mov_b32_e32 v58, v0
	s_add_u32 s12, s3, s12
	s_addc_u32 s13, s8, s13
	v_readfirstlane_b32 s3, v58
	s_ashr_i32 s45, s3, 6
	s_lshl_b32 s24, s45, 5
	s_ashr_i32 s25, s24, 31
	s_lshl_b64 s[24:25], s[24:25], 11
	v_and_b32_e32 v1, 63, v58
	s_add_u32 s70, s6, s24
	s_addc_u32 s71, s7, s25
	v_lshlrev_b32_e32 v206, 8, v1
	s_lshl_b32 s24, s45, 3
	v_lshl_add_u64 v[18:19], s[72:73], 0, v[206:207]
	s_ashr_i32 s25, s24, 31
	v_lshl_add_u64 v[198:199], s[24:25], 1, v[18:19]
	s_lshl_b32 s7, s45, 4
	v_bfe_u32 v18, v58, 2, 4
	v_and_or_b32 v18, s7, 48, v18
	s_and_b32 s6, s3, 0x3fffffc0
	v_lshlrev_b32_e32 v206, 8, v18
	s_ashr_i32 s3, s3, 3
	v_lshl_add_u64 v[18:19], s[12:13], 0, v[206:207]
	s_and_b32 s12, s3, 0xffffffe0
	s_ashr_i32 s13, s12, 31
	s_lshl_b32 s49, s45, 10
	v_lshlrev_b32_e32 v212, 3, v58
	s_cmp_lg_u32 0, -1
	v_and_b32_e32 v215, 24, v212
	s_cselect_b32 s3, 0, 0
	v_lshl_add_u64 v[18:19], s[12:13], 1, v[18:19]
	v_lshlrev_b32_e32 v206, 1, v215
	s_add_i32 s49, s49, s3
	s_mov_b32 s3, m0
	s_mov_b32 m0, s49
	s_nop 0
	global_load_lds_dwordx4 v[198:199], off
	s_mov_b32 m0, s3
	v_and_b32_e32 v213, 31, v58
	v_lshl_add_u64 v[98:99], v[18:19], 0, v[206:207]
	s_add_i32 s61, s49, 0x6000
	s_mov_b32 s3, m0
	s_mov_b32 m0, s61
	s_nop 0
	global_load_lds_dwordx4 v[98:99], off
	s_mov_b32 m0, s3
	v_lshl_add_u64 v[18:19], v[198:199], 0, s[10:11]
	v_bfe_u32 v214, v58, 5, 1
	s_add_i32 s3, s49, 0x2000
	s_mov_b32 s7, m0
	s_mov_b32 m0, s3
	s_nop 0
	global_load_lds_dwordx4 v[18:19], off
	s_mov_b32 m0, s7
	v_lshlrev_b32_e32 v18, 11, v213
	v_lshl_or_b32 v18, v214, 4, v18
	global_load_dwordx4 v[150:153], v18, s[70:71]
	global_load_dwordx4 v[142:145], v18, s[70:71] offset:32
	global_load_dwordx4 v[134:137], v18, s[70:71] offset:64
	global_load_dwordx4 v[130:133], v18, s[70:71] offset:96
	v_mov_b64_e32 v[32:33], v[16:17]
	v_mov_b64_e32 v[30:31], v[14:15]
	v_mov_b64_e32 v[28:29], v[12:13]
	v_mov_b64_e32 v[26:27], v[10:11]
	v_mov_b64_e32 v[24:25], v[8:9]
	v_mov_b64_e32 v[22:23], v[6:7]
	v_mov_b64_e32 v[20:21], v[4:5]
	v_mov_b64_e32 v[18:19], v[2:3]
	v_lshlrev_b32_e32 v34, 10, v214
	v_lshlrev_b32_e32 v35, 4, v213
	v_add3_u32 v219, 0, v34, v35
	v_lshl_add_u64 v[34:35], v[198:199], 0, s[14:15]
	s_add_i32 s3, s49, 0x4000
	s_mov_b32 s7, m0
	s_mov_b32 m0, s3
	s_nop 0
	global_load_lds_dwordx4 v[34:35], off
	s_mov_b32 m0, s7
	s_waitcnt vmcnt(3) lgkmcnt(0)
	s_barrier
	ds_read_b128 v[50:53], v219
	ds_read_b128 v[54:57], v219 offset:512
	v_lshlrev_b32_e32 v59, 1, v58
	v_and_b32_e32 v216, 32, v59
	s_lshl_b32 s3, s6, 2
	s_add_i32 s60, s3, 0
	v_lshl_add_u64 v[200:201], v[98:99], 0, s[10:11]
	v_add_u32_e32 v100, 0, v216
	s_mov_b32 s8, 1
	s_mov_b32 s63, 0
	s_movk_i32 s62, 0x2000
	s_movk_i32 s66, 0x4000
	s_andn2_b64 vcc, exec, s[0:1]
	v_cmp_gt_u32_e64 s[0:1], 32, v1
	v_lshlrev_b32_e32 v221, 4, v214
	v_lshl_add_u32 v217, v213, 2, s60
	s_waitcnt vmcnt(3) lgkmcnt(1)
	v_mfma_f32_32x32x16_bf16 v[34:49], v[50:53], v[150:153], v[18:33]
	s_waitcnt lgkmcnt(0)
	v_mfma_f32_32x32x16_bf16 v[18:33], v[54:57], v[150:153], v[18:33]
	ds_read_b128 v[50:53], v219 offset:2048
	ds_read_b128 v[54:57], v219 offset:2560
	s_waitcnt vmcnt(2) lgkmcnt(1)
	v_mfma_f32_32x32x16_bf16 v[34:49], v[50:53], v[142:145], v[34:49]
	s_waitcnt lgkmcnt(0)
	v_mfma_f32_32x32x16_bf16 v[18:33], v[54:57], v[142:145], v[18:33]
	ds_read_b128 v[50:53], v219 offset:4096
	ds_read_b128 v[54:57], v219 offset:4608
	s_waitcnt vmcnt(1) lgkmcnt(1)
	v_mfma_f32_32x32x16_bf16 v[34:49], v[50:53], v[134:137], v[34:49]
	ds_read_b128 v[50:53], v219 offset:6144
	s_waitcnt lgkmcnt(1)
	v_mfma_f32_32x32x16_bf16 v[18:33], v[54:57], v[134:137], v[18:33]
	ds_read_b128 v[54:57], v219 offset:6656
	s_waitcnt vmcnt(0) lgkmcnt(1)
	v_mfma_f32_32x32x16_bf16 v[34:49], v[50:53], v[130:133], v[34:49]
	v_lshlrev_b32_e32 v50, 4, v58
	v_and_b32_e32 v50, 0xc0, v50
	v_lshl_or_b32 v206, v214, 8, v50
	v_add3_u32 v220, v100, v215, v206
	s_waitcnt lgkmcnt(0)
	v_mfma_f32_32x32x16_bf16 v[18:33], v[54:57], v[130:133], v[18:33]
	s_nop 15
	s_nop 7
	s_nop 0
	v_max3_f32 v50, v34, v35, v18
	v_max3_f32 v51, v36, v37, v19
	s_nop 0
	v_max3_f32 v50, v50, v20, v21
	v_max3_f32 v51, v51, v40, v41
	s_nop 0
	v_max3_f32 v50, v50, v38, v39
	v_max3_f32 v51, v51, v24, v25
	s_nop 0
	v_max3_f32 v50, v50, v22, v23
	v_max3_f32 v51, v51, v44, v45
	s_nop 0
	v_max3_f32 v50, v50, v42, v43
	v_max3_f32 v51, v51, v28, v29
	s_nop 0
	v_max3_f32 v50, v50, v26, v27
	v_max3_f32 v51, v51, v48, v49
	s_nop 0
	v_max3_f32 v50, v50, v46, v47
	v_max3_f32 v51, v51, v32, v33
	s_nop 0
	v_max3_f32 v50, v50, v30, v31
	s_nop 0
	v_max_f32_e32 v50, v50, v51
	s_nop 0
	v_mov_b32_e32 v51, v50
	s_nop 1
	v_permlane32_swap_b32_e32 v50, v51
	v_max_f32_e32 v50, v50, v51
	s_nop 0
	v_add_f32_e32 v218, v207, v50
	v_sub_f32_e32 v34, v34, v50
	v_sub_f32_e32 v18, v18, v50
	v_sub_f32_e32 v35, v35, v50
	v_sub_f32_e32 v19, v19, v50
	v_sub_f32_e32 v36, v36, v50
	v_sub_f32_e32 v20, v20, v50
	v_sub_f32_e32 v37, v37, v50
	v_sub_f32_e32 v21, v21, v50
	v_sub_f32_e32 v38, v38, v50
	v_sub_f32_e32 v22, v22, v50
	v_sub_f32_e32 v39, v39, v50
	v_sub_f32_e32 v23, v23, v50
	v_sub_f32_e32 v40, v40, v50
	v_sub_f32_e32 v24, v24, v50
	v_sub_f32_e32 v41, v41, v50
	v_sub_f32_e32 v25, v25, v50
	v_sub_f32_e32 v42, v42, v50
	v_sub_f32_e32 v26, v26, v50
	v_sub_f32_e32 v43, v43, v50
	v_sub_f32_e32 v27, v27, v50
	v_sub_f32_e32 v44, v44, v50
	v_sub_f32_e32 v28, v28, v50
	v_sub_f32_e32 v45, v45, v50
	v_sub_f32_e32 v29, v29, v50
	v_sub_f32_e32 v46, v46, v50
	v_sub_f32_e32 v30, v30, v50
	v_sub_f32_e32 v47, v47, v50
	v_sub_f32_e32 v31, v31, v50
	v_sub_f32_e32 v48, v48, v50
	v_sub_f32_e32 v32, v32, v50
	v_sub_f32_e32 v49, v49, v50
	v_sub_f32_e32 v33, v33, v50
	s_nop 0
	v_xor_b32_e32 v50, 0x80000000, v218
	v_mov_b32_e32 v51, v50
	v_mov_b32_e32 v52, v50
	v_mov_b32_e32 v53, v50
	v_mov_b32_e32 v54, v50
	v_mov_b32_e32 v55, v50
	v_mov_b32_e32 v56, v50
	v_mov_b32_e32 v57, v50
	v_mov_b32_e32 v58, v50
	v_mov_b32_e32 v59, v50
	v_mov_b32_e32 v60, v50
	v_mov_b32_e32 v61, v50
	v_mov_b32_e32 v62, v50
	v_mov_b32_e32 v63, v50
	v_mov_b32_e32 v64, v50
	v_mov_b32_e32 v65, v50
	s_waitcnt vmcnt(0) lgkmcnt(0)
	s_barrier
	v_exp_f32_e32 v66, v18
	v_exp_f32_e32 v67, v19
	v_lshl_add_u64 v[18:19], v[198:199], 0, s[52:53]
	s_mov_b32 s3, m0
	s_mov_b32 m0, s49
	s_nop 0
	global_load_lds_dwordx4 v[18:19], off
	s_mov_b32 m0, s3
	s_add_i32 s3, s49, 0x8000
	s_mov_b32 s6, m0
	s_mov_b32 m0, s3
	s_nop 0
	global_load_lds_dwordx4 v[200:201], off
	s_mov_b32 m0, s6
	ds_read_b128 v[190:193], v219 offset:8192
	ds_read_b128 v[186:189], v219 offset:8704
	ds_read_b128 v[182:185], v219 offset:10240
	ds_read_b128 v[178:181], v219 offset:10752
	ds_read_b128 v[174:177], v219 offset:12288
	ds_read_b128 v[170:173], v219 offset:12800
	ds_read_b128 v[166:169], v219 offset:14336
	ds_read_b128 v[162:165], v219 offset:14848
	v_exp_f32_e32 v82, v34
	v_exp_f32_e32 v83, v35
	v_exp_f32_e32 v84, v36
	v_exp_f32_e32 v85, v37
	v_exp_f32_e32 v86, v38
	v_exp_f32_e32 v87, v39
	v_exp_f32_e32 v88, v40
	v_exp_f32_e32 v89, v41
	v_exp_f32_e32 v90, v42
	v_exp_f32_e32 v91, v43
	v_exp_f32_e32 v92, v44
	v_exp_f32_e32 v93, v45
	v_exp_f32_e32 v94, v46
	v_exp_f32_e32 v95, v47
	v_exp_f32_e32 v96, v48
	v_exp_f32_e32 v97, v49
	v_exp_f32_e32 v68, v20
	v_exp_f32_e32 v69, v21
	v_exp_f32_e32 v70, v22
	v_exp_f32_e32 v71, v23
	v_exp_f32_e32 v72, v24
	v_exp_f32_e32 v73, v25
	v_exp_f32_e32 v74, v26
	v_exp_f32_e32 v75, v27
	v_exp_f32_e32 v76, v28
	v_exp_f32_e32 v77, v29
	v_exp_f32_e32 v78, v30
	v_exp_f32_e32 v79, v31
	v_exp_f32_e32 v80, v32
	v_exp_f32_e32 v81, v33
	s_waitcnt vmcnt(2) lgkmcnt(0)
	s_barrier
	s_cbranch_vccnz .LBB0_512
	s_mov_b64 s[6:7], 0x14000
	v_mov_b32_e32 v222, 0
	v_lshl_add_u64 v[202:203], v[98:99], 0, s[52:53]
	v_lshl_add_u64 v[204:205], v[198:199], 0, s[6:7]
	s_movk_i32 s63, 0x4000
	s_movk_i32 s12, 0x2000
	s_mov_b32 s6, 0
	s_mov_b32 s8, 6
	v_mov_b32_e32 v34, 0
	v_mov_b32_e32 v35, v222
	v_mov_b32_e32 v36, v222
	v_mov_b32_e32 v37, v222
	v_mov_b32_e32 v38, v222
	v_mov_b32_e32 v39, v222
	v_mov_b32_e32 v40, v222
	v_mov_b32_e32 v41, v222
	v_mov_b32_e32 v42, v222
	v_mov_b32_e32 v43, v222
	v_mov_b32_e32 v44, v222
	v_mov_b32_e32 v45, v222
	v_mov_b32_e32 v46, v222
	v_mov_b32_e32 v47, v222
	v_mov_b32_e32 v48, v222
	v_mov_b32_e32 v49, v222
	v_mov_b32_e32 v18, v222
	v_mov_b32_e32 v19, v222
	v_mov_b32_e32 v20, v222
	v_mov_b32_e32 v21, v222
	v_mov_b32_e32 v22, v222
	v_mov_b32_e32 v23, v222
	v_mov_b32_e32 v24, v222
	v_mov_b32_e32 v25, v222
	v_mov_b32_e32 v26, v222
	v_mov_b32_e32 v27, v222
	v_mov_b32_e32 v28, v222
	v_mov_b32_e32 v29, v222
	v_mov_b32_e32 v30, v222
	v_mov_b32_e32 v31, v222
	v_mov_b32_e32 v32, v222
	v_mov_b32_e32 v33, v222
	.p2alignl 6, 3212836864

.LBB0_520:
	s_lshl_b64 s[0:1], s[8:9], 14
	v_lshl_add_u64 v[208:209], v[200:201], 0, s[0:1]
	v_lshl_add_u64 v[98:99], v[198:199], 0, s[0:1]
	s_mov_b64 s[0:1], 0x10000
	s_add_i32 s67, s48, -2
	v_cmp_gt_u32_e64 s[6:7], 32, v1
	s_add_i32 s8, s8, 2
	v_lshl_add_u64 v[210:211], v[98:99], 0, s[0:1]
	.p2alignl 6, 3212836864

.LBB0_632:
	s_add_i32 s81, s87, -2
	s_add_u32 s88, s88, 0x40080
	s_addc_u32 s89, s89, 0
	s_add_u32 s83, s90, 0x100
	v_mov_b32_e32 v2, 0
	s_addc_u32 vcc_lo, s91, 0
	s_mov_b32 s12, 0
	v_mov_b32_e32 v3, v2
	v_mov_b32_e32 v4, v2
	v_mov_b32_e32 v5, v2
	v_mov_b32_e32 v6, v2
	v_mov_b32_e32 v7, v2
	v_mov_b32_e32 v8, v2
	v_mov_b32_e32 v9, v2
	v_mov_b32_e32 v10, v2
	v_mov_b32_e32 v11, v2
	v_mov_b32_e32 v12, v2
	v_mov_b32_e32 v13, v2
	v_mov_b32_e32 v14, v2
	v_mov_b32_e32 v15, v2
	v_mov_b32_e32 v16, v2
	v_mov_b32_e32 v17, v2
	v_mov_b32_e32 v22, v2
	v_mov_b32_e32 v23, v2
	v_mov_b32_e32 v24, v2
	v_mov_b32_e32 v25, v2
	v_mov_b32_e32 v30, v2
	v_mov_b32_e32 v31, v2
	v_mov_b32_e32 v32, v2
	v_mov_b32_e32 v33, v2
	v_mov_b32_e32 v38, v2
	v_mov_b32_e32 v39, v2
	v_mov_b32_e32 v40, v2
	v_mov_b32_e32 v41, v2
	v_mov_b32_e32 v46, v2
	v_mov_b32_e32 v47, v2
	v_mov_b32_e32 v48, v2
	v_mov_b32_e32 v49, v2
	v_mov_b32_e32 v18, v2
	v_mov_b32_e32 v19, v2
	v_mov_b32_e32 v20, v2
	v_mov_b32_e32 v21, v2
	v_mov_b32_e32 v26, v2
	v_mov_b32_e32 v27, v2
	v_mov_b32_e32 v28, v2
	v_mov_b32_e32 v29, v2
	v_mov_b32_e32 v34, v2
	v_mov_b32_e32 v35, v2
	v_mov_b32_e32 v36, v2
	v_mov_b32_e32 v37, v2
	v_mov_b32_e32 v42, v2
	v_mov_b32_e32 v43, v2
	v_mov_b32_e32 v44, v2
	v_mov_b32_e32 v45, v2
	v_mov_b32_e32 v50, v2
	v_mov_b32_e32 v51, v2
	v_mov_b32_e32 v52, v2
	v_mov_b32_e32 v53, v2
	v_mov_b32_e32 v54, v2
	v_mov_b32_e32 v55, v2
	v_mov_b32_e32 v56, v2
	v_mov_b32_e32 v57, v2
	v_mov_b32_e32 v58, v2
	v_mov_b32_e32 v59, v2
	v_mov_b32_e32 v60, v2
	v_mov_b32_e32 v61, v2
	v_mov_b32_e32 v62, v2
	v_mov_b32_e32 v63, v2
	v_mov_b32_e32 v64, v2
	v_mov_b32_e32 v65, v2
	v_mov_b32_e32 v66, v2
	v_mov_b32_e32 v67, v2
	v_mov_b32_e32 v68, v2
	v_mov_b32_e32 v69, v2
	v_mov_b32_e32 v70, v2
	v_mov_b32_e32 v71, v2
	v_mov_b32_e32 v72, v2
	v_mov_b32_e32 v73, v2
	v_mov_b32_e32 v74, v2
	v_mov_b32_e32 v75, v2
	v_mov_b32_e32 v76, v2
	v_mov_b32_e32 v77, v2
	v_mov_b32_e32 v78, v2
	v_mov_b32_e32 v79, v2
	v_mov_b32_e32 v80, v2
	v_mov_b32_e32 v81, v2
	v_mov_b32_e32 v86, v2
	v_mov_b32_e32 v87, v2
	v_mov_b32_e32 v88, v2
	v_mov_b32_e32 v89, v2
	v_mov_b32_e32 v94, v2
	v_mov_b32_e32 v95, v2
	v_mov_b32_e32 v96, v2
	v_mov_b32_e32 v97, v2
	v_mov_b32_e32 v102, v2
	v_mov_b32_e32 v103, v2
	v_mov_b32_e32 v104, v2
	v_mov_b32_e32 v105, v2
	v_mov_b32_e32 v110, v2
	v_mov_b32_e32 v111, v2
	v_mov_b32_e32 v112, v2
	v_mov_b32_e32 v113, v2
	v_mov_b32_e32 v82, v2
	v_mov_b32_e32 v83, v2
	v_mov_b32_e32 v84, v2
	v_mov_b32_e32 v85, v2
	v_mov_b32_e32 v90, v2
	v_mov_b32_e32 v91, v2
	v_mov_b32_e32 v92, v2
	v_mov_b32_e32 v93, v2
	v_mov_b32_e32 v98, v2
	v_mov_b32_e32 v99, v2
	v_mov_b32_e32 v100, v2
	v_mov_b32_e32 v101, v2
	v_mov_b32_e32 v106, v2
	v_mov_b32_e32 v107, v2
	v_mov_b32_e32 v108, v2
	v_mov_b32_e32 v109, v2
	v_mov_b32_e32 v114, v2
	v_mov_b32_e32 v115, v2
	v_mov_b32_e32 v116, v2
	v_mov_b32_e32 v117, v2
	v_mov_b32_e32 v118, v2
	v_mov_b32_e32 v119, v2
	v_mov_b32_e32 v120, v2
	v_mov_b32_e32 v121, v2
	v_mov_b32_e32 v122, v2
	v_mov_b32_e32 v123, v2
	v_mov_b32_e32 v124, v2
	v_mov_b32_e32 v125, v2
	v_mov_b32_e32 v126, v2
	v_mov_b32_e32 v127, v2
	v_mov_b32_e32 v128, v2
	v_mov_b32_e32 v129, v2
	.p2alignl 6, 3212836864

.LBB0_662:
	s_ashr_i32 s73, s72, 31
	s_lshl_b64 s[12:13], s[72:73], 19
	v_cmp_lt_i64_e32 vcc, s[74:75], v[150:151]
	s_add_u32 s74, s19, s12
	s_addc_u32 s75, s27, s13
	s_and_b64 s[12:13], vcc, exec
	s_cselect_b32 s37, s75, s83
	s_cselect_b32 s49, s74, s82
	s_ashr_i32 s71, s70, 31
	s_lshl_b64 s[12:13], s[70:71], 19
	s_add_u32 s76, s66, s12
	s_addc_u32 s77, s67, s13
	s_and_b64 s[12:13], vcc, exec
	s_cselect_b32 s71, s77, s85
	s_cselect_b32 s73, s76, s84
	s_add_u32 s82, s82, 0x40080
	s_addc_u32 s83, s83, 0
	s_add_u32 s79, s84, 0x100
	v_mov_b32_e32 v2, 0
	s_addc_u32 vcc_lo, s85, 0
	s_mov_b32 s12, -2
	s_waitcnt lgkmcnt(0)
	v_mov_b32_e32 v3, v2
	v_mov_b32_e32 v4, v2
	v_mov_b32_e32 v5, v2
	v_mov_b32_e32 v6, v2
	v_mov_b32_e32 v7, v2
	v_mov_b32_e32 v8, v2
	v_mov_b32_e32 v9, v2
	v_mov_b32_e32 v10, v2
	v_mov_b32_e32 v11, v2
	v_mov_b32_e32 v12, v2
	v_mov_b32_e32 v13, v2
	v_mov_b32_e32 v14, v2
	v_mov_b32_e32 v15, v2
	v_mov_b32_e32 v16, v2
	v_mov_b32_e32 v17, v2
	v_mov_b32_e32 v18, v2
	v_mov_b32_e32 v19, v2
	v_mov_b32_e32 v20, v2
	v_mov_b32_e32 v21, v2
	v_mov_b32_e32 v22, v2
	v_mov_b32_e32 v23, v2
	v_mov_b32_e32 v24, v2
	v_mov_b32_e32 v25, v2
	v_mov_b32_e32 v26, v2
	v_mov_b32_e32 v27, v2
	v_mov_b32_e32 v28, v2
	v_mov_b32_e32 v29, v2
	v_mov_b32_e32 v30, v2
	v_mov_b32_e32 v31, v2
	v_mov_b32_e32 v32, v2
	v_mov_b32_e32 v33, v2
	v_mov_b32_e32 v66, v2
	v_mov_b32_e32 v67, v2
	v_mov_b32_e32 v68, v2
	v_mov_b32_e32 v69, v2
	v_mov_b32_e32 v70, v2
	v_mov_b32_e32 v71, v2
	v_mov_b32_e32 v72, v2
	v_mov_b32_e32 v73, v2
	v_mov_b32_e32 v74, v2
	v_mov_b32_e32 v75, v2
	v_mov_b32_e32 v76, v2
	v_mov_b32_e32 v77, v2
	v_mov_b32_e32 v78, v2
	v_mov_b32_e32 v79, v2
	v_mov_b32_e32 v80, v2
	v_mov_b32_e32 v81, v2
	v_mov_b32_e32 v82, v2
	v_mov_b32_e32 v83, v2
	v_mov_b32_e32 v84, v2
	v_mov_b32_e32 v85, v2
	v_mov_b32_e32 v86, v2
	v_mov_b32_e32 v87, v2
	v_mov_b32_e32 v88, v2
	v_mov_b32_e32 v89, v2
	v_mov_b32_e32 v90, v2
	v_mov_b32_e32 v91, v2
	v_mov_b32_e32 v92, v2
	v_mov_b32_e32 v93, v2
	v_mov_b32_e32 v94, v2
	v_mov_b32_e32 v95, v2
	v_mov_b32_e32 v96, v2
	v_mov_b32_e32 v97, v2
	v_mov_b32_e32 v34, v2
	v_mov_b32_e32 v35, v2
	v_mov_b32_e32 v36, v2
	v_mov_b32_e32 v37, v2
	v_mov_b32_e32 v38, v2
	v_mov_b32_e32 v39, v2
	v_mov_b32_e32 v40, v2
	v_mov_b32_e32 v41, v2
	v_mov_b32_e32 v42, v2
	v_mov_b32_e32 v43, v2
	v_mov_b32_e32 v44, v2
	v_mov_b32_e32 v45, v2
	v_mov_b32_e32 v46, v2
	v_mov_b32_e32 v47, v2
	v_mov_b32_e32 v48, v2
	v_mov_b32_e32 v49, v2
	v_mov_b32_e32 v50, v2
	v_mov_b32_e32 v51, v2
	v_mov_b32_e32 v52, v2
	v_mov_b32_e32 v53, v2
	v_mov_b32_e32 v54, v2
	v_mov_b32_e32 v55, v2
	v_mov_b32_e32 v56, v2
	v_mov_b32_e32 v57, v2
	v_mov_b32_e32 v58, v2
	v_mov_b32_e32 v59, v2
	v_mov_b32_e32 v60, v2
	v_mov_b32_e32 v61, v2
	v_mov_b32_e32 v62, v2
	v_mov_b32_e32 v63, v2
	v_mov_b32_e32 v64, v2
	v_mov_b32_e32 v65, v2
	v_mov_b32_e32 v106, v2
	v_mov_b32_e32 v107, v2
	v_mov_b32_e32 v108, v2
	v_mov_b32_e32 v109, v2
	v_mov_b32_e32 v110, v2
	v_mov_b32_e32 v111, v2
	v_mov_b32_e32 v112, v2
	v_mov_b32_e32 v113, v2
	v_mov_b32_e32 v114, v2
	v_mov_b32_e32 v115, v2
	v_mov_b32_e32 v116, v2
	v_mov_b32_e32 v117, v2
	v_mov_b32_e32 v118, v2
	v_mov_b32_e32 v119, v2
	v_mov_b32_e32 v120, v2
	v_mov_b32_e32 v121, v2
	v_mov_b32_e32 v122, v2
	v_mov_b32_e32 v123, v2
	v_mov_b32_e32 v124, v2
	v_mov_b32_e32 v125, v2
	v_mov_b32_e32 v126, v2
	v_mov_b32_e32 v127, v2
	v_mov_b32_e32 v128, v2
	v_mov_b32_e32 v129, v2
	v_mov_b32_e32 v130, v2
	v_mov_b32_e32 v131, v2
	v_mov_b32_e32 v132, v2
	v_mov_b32_e32 v133, v2
	v_mov_b32_e32 v134, v2
	v_mov_b32_e32 v135, v2
	v_mov_b32_e32 v136, v2
	v_mov_b32_e32 v137, v2
	.p2alignl 6, 3212836864

.LBB0_776:
	s_ashr_i32 s75, s74, 31
	s_lshl_b64 s[12:13], s[74:75], 19
	s_add_u32 s80, s4, s12
	s_addc_u32 s81, s5, s13
	s_and_b64 s[12:13], s[78:79], exec
	s_cselect_b32 s11, s81, s85
	s_cselect_b32 s37, s80, s84
	s_ashr_i32 s77, s76, 31
	s_lshl_b64 s[12:13], s[76:77], 19
	s_add_u32 s82, s19, s12
	s_addc_u32 s83, s22, s13
	s_and_b64 s[12:13], s[78:79], exec
	s_cselect_b32 s75, s83, s87
	s_cselect_b32 s77, s82, s86
	s_add_u32 s84, s84, 0x40080
	s_addc_u32 s85, s85, 0
	s_add_u32 s92, s86, 0x100
	v_mov_b32_e32 v2, 0
	s_addc_u32 s93, s87, 0
	s_mov_b32 s12, -2
	v_mov_b32_e32 v3, v2
	v_mov_b32_e32 v4, v2
	v_mov_b32_e32 v5, v2
	v_mov_b32_e32 v6, v2
	v_mov_b32_e32 v7, v2
	v_mov_b32_e32 v8, v2
	v_mov_b32_e32 v9, v2
	v_mov_b32_e32 v18, v2
	v_mov_b32_e32 v19, v2
	v_mov_b32_e32 v20, v2
	v_mov_b32_e32 v21, v2
	v_mov_b32_e32 v22, v2
	v_mov_b32_e32 v23, v2
	v_mov_b32_e32 v24, v2
	v_mov_b32_e32 v25, v2
	v_mov_b32_e32 v34, v2
	v_mov_b32_e32 v35, v2
	v_mov_b32_e32 v36, v2
	v_mov_b32_e32 v37, v2
	v_mov_b32_e32 v38, v2
	v_mov_b32_e32 v39, v2
	v_mov_b32_e32 v40, v2
	v_mov_b32_e32 v41, v2
	v_mov_b32_e32 v66, v2
	v_mov_b32_e32 v67, v2
	v_mov_b32_e32 v68, v2
	v_mov_b32_e32 v69, v2
	v_mov_b32_e32 v70, v2
	v_mov_b32_e32 v71, v2
	v_mov_b32_e32 v72, v2
	v_mov_b32_e32 v73, v2
	v_mov_b32_e32 v10, v2
	v_mov_b32_e32 v11, v2
	v_mov_b32_e32 v12, v2
	v_mov_b32_e32 v13, v2
	v_mov_b32_e32 v14, v2
	v_mov_b32_e32 v15, v2
	v_mov_b32_e32 v16, v2
	v_mov_b32_e32 v17, v2
	v_mov_b32_e32 v26, v2
	v_mov_b32_e32 v27, v2
	v_mov_b32_e32 v28, v2
	v_mov_b32_e32 v29, v2
	v_mov_b32_e32 v30, v2
	v_mov_b32_e32 v31, v2
	v_mov_b32_e32 v32, v2
	v_mov_b32_e32 v33, v2
	v_mov_b32_e32 v42, v2
	v_mov_b32_e32 v43, v2
	v_mov_b32_e32 v44, v2
	v_mov_b32_e32 v45, v2
	v_mov_b32_e32 v46, v2
	v_mov_b32_e32 v47, v2
	v_mov_b32_e32 v48, v2
	v_mov_b32_e32 v49, v2
	v_mov_b32_e32 v74, v2
	v_mov_b32_e32 v75, v2
	v_mov_b32_e32 v76, v2
	v_mov_b32_e32 v77, v2
	v_mov_b32_e32 v78, v2
	v_mov_b32_e32 v79, v2
	v_mov_b32_e32 v80, v2
	v_mov_b32_e32 v81, v2
	v_mov_b32_e32 v82, v2
	v_mov_b32_e32 v83, v2
	v_mov_b32_e32 v84, v2
	v_mov_b32_e32 v85, v2
	v_mov_b32_e32 v86, v2
	v_mov_b32_e32 v87, v2
	v_mov_b32_e32 v88, v2
	v_mov_b32_e32 v89, v2
	v_mov_b32_e32 v98, v2
	v_mov_b32_e32 v99, v2
	v_mov_b32_e32 v100, v2
	v_mov_b32_e32 v101, v2
	v_mov_b32_e32 v102, v2
	v_mov_b32_e32 v103, v2
	v_mov_b32_e32 v104, v2
	v_mov_b32_e32 v105, v2
	v_mov_b32_e32 v114, v2
	v_mov_b32_e32 v115, v2
	v_mov_b32_e32 v116, v2
	v_mov_b32_e32 v117, v2
	v_mov_b32_e32 v118, v2
	v_mov_b32_e32 v119, v2
	v_mov_b32_e32 v120, v2
	v_mov_b32_e32 v121, v2
	v_mov_b32_e32 v130, v2
	v_mov_b32_e32 v131, v2
	v_mov_b32_e32 v132, v2
	v_mov_b32_e32 v133, v2
	v_mov_b32_e32 v134, v2
	v_mov_b32_e32 v135, v2
	v_mov_b32_e32 v136, v2
	v_mov_b32_e32 v137, v2
	v_mov_b32_e32 v90, v2
	v_mov_b32_e32 v91, v2
	v_mov_b32_e32 v92, v2
	v_mov_b32_e32 v93, v2
	v_mov_b32_e32 v94, v2
	v_mov_b32_e32 v95, v2
	v_mov_b32_e32 v96, v2
	v_mov_b32_e32 v97, v2
	v_mov_b32_e32 v106, v2
	v_mov_b32_e32 v107, v2
	v_mov_b32_e32 v108, v2
	v_mov_b32_e32 v109, v2
	v_mov_b32_e32 v110, v2
	v_mov_b32_e32 v111, v2
	v_mov_b32_e32 v112, v2
	v_mov_b32_e32 v113, v2
	v_mov_b32_e32 v122, v2
	v_mov_b32_e32 v123, v2
	v_mov_b32_e32 v124, v2
	v_mov_b32_e32 v125, v2
	v_mov_b32_e32 v126, v2
	v_mov_b32_e32 v127, v2
	v_mov_b32_e32 v128, v2
	v_mov_b32_e32 v129, v2
	v_mov_b32_e32 v138, v2
	v_mov_b32_e32 v139, v2
	v_mov_b32_e32 v140, v2
	v_mov_b32_e32 v141, v2
	v_mov_b32_e32 v142, v2
	v_mov_b32_e32 v143, v2
	v_mov_b32_e32 v144, v2
	v_mov_b32_e32 v145, v2
	.p2alignl 6, 3212836864

.LBB0_817:
	s_add_i32 s80, s21, -2
	s_add_u32 s81, s70, 0x100
	v_mov_b32_e32 v2, 0
	s_addc_u32 s82, s71, 0
	s_mov_b32 s12, 0
	v_mov_b32_e32 v3, v2
	v_mov_b32_e32 v4, v2
	v_mov_b32_e32 v5, v2
	v_mov_b32_e32 v6, v2
	v_mov_b32_e32 v7, v2
	v_mov_b32_e32 v8, v2
	v_mov_b32_e32 v9, v2
	v_mov_b32_e32 v10, v2
	v_mov_b32_e32 v11, v2
	v_mov_b32_e32 v12, v2
	v_mov_b32_e32 v13, v2
	v_mov_b32_e32 v14, v2
	v_mov_b32_e32 v15, v2
	v_mov_b32_e32 v16, v2
	v_mov_b32_e32 v17, v2
	v_mov_b32_e32 v18, v2
	v_mov_b32_e32 v19, v2
	v_mov_b32_e32 v20, v2
	v_mov_b32_e32 v21, v2
	v_mov_b32_e32 v26, v2
	v_mov_b32_e32 v27, v2
	v_mov_b32_e32 v28, v2
	v_mov_b32_e32 v29, v2
	v_mov_b32_e32 v34, v2
	v_mov_b32_e32 v35, v2
	v_mov_b32_e32 v36, v2
	v_mov_b32_e32 v37, v2
	v_mov_b32_e32 v42, v2
	v_mov_b32_e32 v43, v2
	v_mov_b32_e32 v44, v2
	v_mov_b32_e32 v45, v2
	v_mov_b32_e32 v22, v2
	v_mov_b32_e32 v23, v2
	v_mov_b32_e32 v24, v2
	v_mov_b32_e32 v25, v2
	v_mov_b32_e32 v30, v2
	v_mov_b32_e32 v31, v2
	v_mov_b32_e32 v32, v2
	v_mov_b32_e32 v33, v2
	v_mov_b32_e32 v38, v2
	v_mov_b32_e32 v39, v2
	v_mov_b32_e32 v40, v2
	v_mov_b32_e32 v41, v2
	v_mov_b32_e32 v46, v2
	v_mov_b32_e32 v47, v2
	v_mov_b32_e32 v48, v2
	v_mov_b32_e32 v49, v2
	v_mov_b32_e32 v50, v2
	v_mov_b32_e32 v51, v2
	v_mov_b32_e32 v52, v2
	v_mov_b32_e32 v53, v2
	v_mov_b32_e32 v54, v2
	v_mov_b32_e32 v55, v2
	v_mov_b32_e32 v56, v2
	v_mov_b32_e32 v57, v2
	v_mov_b32_e32 v58, v2
	v_mov_b32_e32 v59, v2
	v_mov_b32_e32 v60, v2
	v_mov_b32_e32 v61, v2
	v_mov_b32_e32 v62, v2
	v_mov_b32_e32 v63, v2
	v_mov_b32_e32 v64, v2
	v_mov_b32_e32 v65, v2
	v_mov_b32_e32 v66, v2
	v_mov_b32_e32 v67, v2
	v_mov_b32_e32 v68, v2
	v_mov_b32_e32 v69, v2
	v_mov_b32_e32 v70, v2
	v_mov_b32_e32 v71, v2
	v_mov_b32_e32 v72, v2
	v_mov_b32_e32 v73, v2
	v_mov_b32_e32 v74, v2
	v_mov_b32_e32 v75, v2
	v_mov_b32_e32 v76, v2
	v_mov_b32_e32 v77, v2
	v_mov_b32_e32 v78, v2
	v_mov_b32_e32 v79, v2
	v_mov_b32_e32 v80, v2
	v_mov_b32_e32 v81, v2
	v_mov_b32_e32 v82, v2
	v_mov_b32_e32 v83, v2
	v_mov_b32_e32 v84, v2
	v_mov_b32_e32 v85, v2
	v_mov_b32_e32 v90, v2
	v_mov_b32_e32 v91, v2
	v_mov_b32_e32 v92, v2
	v_mov_b32_e32 v93, v2
	v_mov_b32_e32 v98, v2
	v_mov_b32_e32 v99, v2
	v_mov_b32_e32 v100, v2
	v_mov_b32_e32 v101, v2
	v_mov_b32_e32 v106, v2
	v_mov_b32_e32 v107, v2
	v_mov_b32_e32 v108, v2
	v_mov_b32_e32 v109, v2
	v_mov_b32_e32 v86, v2
	v_mov_b32_e32 v87, v2
	v_mov_b32_e32 v88, v2
	v_mov_b32_e32 v89, v2
	v_mov_b32_e32 v94, v2
	v_mov_b32_e32 v95, v2
	v_mov_b32_e32 v96, v2
	v_mov_b32_e32 v97, v2
	v_mov_b32_e32 v102, v2
	v_mov_b32_e32 v103, v2
	v_mov_b32_e32 v104, v2
	v_mov_b32_e32 v105, v2
	v_mov_b32_e32 v110, v2
	v_mov_b32_e32 v111, v2
	v_mov_b32_e32 v112, v2
	v_mov_b32_e32 v113, v2
	v_mov_b32_e32 v114, v2
	v_mov_b32_e32 v115, v2
	v_mov_b32_e32 v116, v2
	v_mov_b32_e32 v117, v2
	v_mov_b32_e32 v118, v2
	v_mov_b32_e32 v119, v2
	v_mov_b32_e32 v120, v2
	v_mov_b32_e32 v121, v2
	v_mov_b32_e32 v122, v2
	v_mov_b32_e32 v123, v2
	v_mov_b32_e32 v124, v2
	v_mov_b32_e32 v125, v2
	v_mov_b32_e32 v126, v2
	v_mov_b32_e32 v127, v2
	v_mov_b32_e32 v128, v2
	v_mov_b32_e32 v129, v2
	.p2alignl 6, 3212836864

.LBB0_903:
	s_add_u32 s69, s72, 0x100
	v_mov_b32_e32 v2, 0
	s_addc_u32 s87, s73, 0
	s_mov_b32 s12, -2
	s_waitcnt lgkmcnt(0)
	v_mov_b32_e32 v3, v2
	v_mov_b32_e32 v4, v2
	v_mov_b32_e32 v5, v2
	v_mov_b32_e32 v6, v2
	v_mov_b32_e32 v7, v2
	v_mov_b32_e32 v8, v2
	v_mov_b32_e32 v9, v2
	v_mov_b32_e32 v10, v2
	v_mov_b32_e32 v11, v2
	v_mov_b32_e32 v12, v2
	v_mov_b32_e32 v13, v2
	v_mov_b32_e32 v14, v2
	v_mov_b32_e32 v15, v2
	v_mov_b32_e32 v16, v2
	v_mov_b32_e32 v17, v2
	v_mov_b32_e32 v18, v2
	v_mov_b32_e32 v19, v2
	v_mov_b32_e32 v20, v2
	v_mov_b32_e32 v21, v2
	v_mov_b32_e32 v22, v2
	v_mov_b32_e32 v23, v2
	v_mov_b32_e32 v24, v2
	v_mov_b32_e32 v25, v2
	v_mov_b32_e32 v26, v2
	v_mov_b32_e32 v27, v2
	v_mov_b32_e32 v28, v2
	v_mov_b32_e32 v29, v2
	v_mov_b32_e32 v30, v2
	v_mov_b32_e32 v31, v2
	v_mov_b32_e32 v32, v2
	v_mov_b32_e32 v33, v2
	v_mov_b32_e32 v66, v2
	v_mov_b32_e32 v67, v2
	v_mov_b32_e32 v68, v2
	v_mov_b32_e32 v69, v2
	v_mov_b32_e32 v70, v2
	v_mov_b32_e32 v71, v2
	v_mov_b32_e32 v72, v2
	v_mov_b32_e32 v73, v2
	v_mov_b32_e32 v74, v2
	v_mov_b32_e32 v75, v2
	v_mov_b32_e32 v76, v2
	v_mov_b32_e32 v77, v2
	v_mov_b32_e32 v78, v2
	v_mov_b32_e32 v79, v2
	v_mov_b32_e32 v80, v2
	v_mov_b32_e32 v81, v2
	v_mov_b32_e32 v82, v2
	v_mov_b32_e32 v83, v2
	v_mov_b32_e32 v84, v2
	v_mov_b32_e32 v85, v2
	v_mov_b32_e32 v86, v2
	v_mov_b32_e32 v87, v2
	v_mov_b32_e32 v88, v2
	v_mov_b32_e32 v89, v2
	v_mov_b32_e32 v90, v2
	v_mov_b32_e32 v91, v2
	v_mov_b32_e32 v92, v2
	v_mov_b32_e32 v93, v2
	v_mov_b32_e32 v94, v2
	v_mov_b32_e32 v95, v2
	v_mov_b32_e32 v96, v2
	v_mov_b32_e32 v97, v2
	v_mov_b32_e32 v34, v2
	v_mov_b32_e32 v35, v2
	v_mov_b32_e32 v36, v2
	v_mov_b32_e32 v37, v2
	v_mov_b32_e32 v38, v2
	v_mov_b32_e32 v39, v2
	v_mov_b32_e32 v40, v2
	v_mov_b32_e32 v41, v2
	v_mov_b32_e32 v42, v2
	v_mov_b32_e32 v43, v2
	v_mov_b32_e32 v44, v2
	v_mov_b32_e32 v45, v2
	v_mov_b32_e32 v46, v2
	v_mov_b32_e32 v47, v2
	v_mov_b32_e32 v48, v2
	v_mov_b32_e32 v49, v2
	v_mov_b32_e32 v50, v2
	v_mov_b32_e32 v51, v2
	v_mov_b32_e32 v52, v2
	v_mov_b32_e32 v53, v2
	v_mov_b32_e32 v54, v2
	v_mov_b32_e32 v55, v2
	v_mov_b32_e32 v56, v2
	v_mov_b32_e32 v57, v2
	v_mov_b32_e32 v58, v2
	v_mov_b32_e32 v59, v2
	v_mov_b32_e32 v60, v2
	v_mov_b32_e32 v61, v2
	v_mov_b32_e32 v62, v2
	v_mov_b32_e32 v63, v2
	v_mov_b32_e32 v64, v2
	v_mov_b32_e32 v65, v2
	v_mov_b32_e32 v98, v2
	v_mov_b32_e32 v99, v2
	v_mov_b32_e32 v100, v2
	v_mov_b32_e32 v101, v2
	v_mov_b32_e32 v102, v2
	v_mov_b32_e32 v103, v2
	v_mov_b32_e32 v104, v2
	v_mov_b32_e32 v105, v2
	v_mov_b32_e32 v106, v2
	v_mov_b32_e32 v107, v2
	v_mov_b32_e32 v108, v2
	v_mov_b32_e32 v109, v2
	v_mov_b32_e32 v110, v2
	v_mov_b32_e32 v111, v2
	v_mov_b32_e32 v112, v2
	v_mov_b32_e32 v113, v2
	v_mov_b32_e32 v114, v2
	v_mov_b32_e32 v115, v2
	v_mov_b32_e32 v116, v2
	v_mov_b32_e32 v117, v2
	v_mov_b32_e32 v118, v2
	v_mov_b32_e32 v119, v2
	v_mov_b32_e32 v120, v2
	v_mov_b32_e32 v121, v2
	v_mov_b32_e32 v122, v2
	v_mov_b32_e32 v123, v2
	v_mov_b32_e32 v124, v2
	v_mov_b32_e32 v125, v2
	v_mov_b32_e32 v126, v2
	v_mov_b32_e32 v127, v2
	v_mov_b32_e32 v128, v2
	v_mov_b32_e32 v129, v2
	.p2alignl 6, 3212836864

.LBB0_990:
	s_ashr_i32 s79, s78, 31
	s_lshl_b64 s[12:13], s[78:79], 19
	s_add_u32 s80, s19, s12
	s_addc_u32 s81, s27, s13
	s_and_b64 s[12:13], s[6:7], exec
	s_cselect_b32 s11, s81, s1
	s_cselect_b32 s23, s80, s0
	s_ashr_i32 s77, s76, 31
	s_lshl_b64 s[12:13], s[76:77], 19
	s_add_u32 s82, s36, s12
	s_addc_u32 s83, s37, s13
	s_and_b64 s[12:13], s[6:7], exec
	s_cselect_b32 s48, s83, s85
	s_cselect_b32 s49, s82, s84
	s_add_u32 s0, s0, 0x40080
	s_addc_u32 s1, s1, 0
	s_add_u32 s63, s84, 0x100
	v_mov_b32_e32 v2, 0
	s_addc_u32 s77, s85, 0
	s_mov_b32 s12, -2
	v_mov_b32_e32 v3, v2
	v_mov_b32_e32 v4, v2
	v_mov_b32_e32 v5, v2
	v_mov_b32_e32 v6, v2
	v_mov_b32_e32 v7, v2
	v_mov_b32_e32 v8, v2
	v_mov_b32_e32 v9, v2
	v_mov_b32_e32 v18, v2
	v_mov_b32_e32 v19, v2
	v_mov_b32_e32 v20, v2
	v_mov_b32_e32 v21, v2
	v_mov_b32_e32 v22, v2
	v_mov_b32_e32 v23, v2
	v_mov_b32_e32 v24, v2
	v_mov_b32_e32 v25, v2
	v_mov_b32_e32 v50, v2
	v_mov_b32_e32 v51, v2
	v_mov_b32_e32 v52, v2
	v_mov_b32_e32 v53, v2
	v_mov_b32_e32 v54, v2
	v_mov_b32_e32 v55, v2
	v_mov_b32_e32 v56, v2
	v_mov_b32_e32 v57, v2
	v_mov_b32_e32 v66, v2
	v_mov_b32_e32 v67, v2
	v_mov_b32_e32 v68, v2
	v_mov_b32_e32 v69, v2
	v_mov_b32_e32 v70, v2
	v_mov_b32_e32 v71, v2
	v_mov_b32_e32 v72, v2
	v_mov_b32_e32 v73, v2
	v_mov_b32_e32 v10, v2
	v_mov_b32_e32 v11, v2
	v_mov_b32_e32 v12, v2
	v_mov_b32_e32 v13, v2
	v_mov_b32_e32 v14, v2
	v_mov_b32_e32 v15, v2
	v_mov_b32_e32 v16, v2
	v_mov_b32_e32 v17, v2
	v_mov_b32_e32 v26, v2
	v_mov_b32_e32 v27, v2
	v_mov_b32_e32 v28, v2
	v_mov_b32_e32 v29, v2
	v_mov_b32_e32 v30, v2
	v_mov_b32_e32 v31, v2
	v_mov_b32_e32 v32, v2
	v_mov_b32_e32 v33, v2
	v_mov_b32_e32 v58, v2
	v_mov_b32_e32 v59, v2
	v_mov_b32_e32 v60, v2
	v_mov_b32_e32 v61, v2
	v_mov_b32_e32 v62, v2
	v_mov_b32_e32 v63, v2
	v_mov_b32_e32 v64, v2
	v_mov_b32_e32 v65, v2
	v_mov_b32_e32 v74, v2
	v_mov_b32_e32 v75, v2
	v_mov_b32_e32 v76, v2
	v_mov_b32_e32 v77, v2
	v_mov_b32_e32 v78, v2
	v_mov_b32_e32 v79, v2
	v_mov_b32_e32 v80, v2
	v_mov_b32_e32 v81, v2
	v_mov_b32_e32 v82, v2
	v_mov_b32_e32 v83, v2
	v_mov_b32_e32 v84, v2
	v_mov_b32_e32 v85, v2
	v_mov_b32_e32 v86, v2
	v_mov_b32_e32 v87, v2
	v_mov_b32_e32 v88, v2
	v_mov_b32_e32 v89, v2
	v_mov_b32_e32 v98, v2
	v_mov_b32_e32 v99, v2
	v_mov_b32_e32 v100, v2
	v_mov_b32_e32 v101, v2
	v_mov_b32_e32 v102, v2
	v_mov_b32_e32 v103, v2
	v_mov_b32_e32 v104, v2
	v_mov_b32_e32 v105, v2
	v_mov_b32_e32 v114, v2
	v_mov_b32_e32 v115, v2
	v_mov_b32_e32 v116, v2
	v_mov_b32_e32 v117, v2
	v_mov_b32_e32 v118, v2
	v_mov_b32_e32 v119, v2
	v_mov_b32_e32 v120, v2
	v_mov_b32_e32 v121, v2
	v_mov_b32_e32 v130, v2
	v_mov_b32_e32 v131, v2
	v_mov_b32_e32 v132, v2
	v_mov_b32_e32 v133, v2
	v_mov_b32_e32 v134, v2
	v_mov_b32_e32 v135, v2
	v_mov_b32_e32 v136, v2
	v_mov_b32_e32 v137, v2
	v_mov_b32_e32 v90, v2
	v_mov_b32_e32 v91, v2
	v_mov_b32_e32 v92, v2
	v_mov_b32_e32 v93, v2
	v_mov_b32_e32 v94, v2
	v_mov_b32_e32 v95, v2
	v_mov_b32_e32 v96, v2
	v_mov_b32_e32 v97, v2
	v_mov_b32_e32 v106, v2
	v_mov_b32_e32 v107, v2
	v_mov_b32_e32 v108, v2
	v_mov_b32_e32 v109, v2
	v_mov_b32_e32 v110, v2
	v_mov_b32_e32 v111, v2
	v_mov_b32_e32 v112, v2
	v_mov_b32_e32 v113, v2
	v_mov_b32_e32 v122, v2
	v_mov_b32_e32 v123, v2
	v_mov_b32_e32 v124, v2
	v_mov_b32_e32 v125, v2
	v_mov_b32_e32 v126, v2
	v_mov_b32_e32 v127, v2
	v_mov_b32_e32 v128, v2
	v_mov_b32_e32 v129, v2
	v_mov_b32_e32 v138, v2
	v_mov_b32_e32 v139, v2
	v_mov_b32_e32 v140, v2
	v_mov_b32_e32 v141, v2
	v_mov_b32_e32 v142, v2
	v_mov_b32_e32 v143, v2
	v_mov_b32_e32 v144, v2
	v_mov_b32_e32 v145, v2
	.p2alignl 6, 3212836864

.LBB0_1277:
	s_bfe_u32 s3, s4, 0x30005
	s_lshl_b32 s5, s3, 22
	s_add_u32 s5, s19, s5
	s_addc_u32 s12, s42, 0
	s_lshl_b32 s13, s4, 19
	s_and_b32 s13, s13, 0x380000
	s_add_u32 s5, s5, s13
	s_addc_u32 s33, s12, 0
	s_lshl_b32 s12, s4, 3
	s_and_b32 s12, s12, 0xc0
	s_and_b32 s13, s4, 0xffffff00
	s_or_b32 s12, s12, s13
	s_ashr_i32 s13, s12, 31
	s_lshl_b64 s[12:13], s[12:13], 1
	s_add_u32 s36, s5, s12
	s_addc_u32 s37, s33, s13
	s_mul_i32 s3, s3, 0x90000
	s_add_u32 s12, s43, s3
	s_addc_u32 s13, s44, 0
	s_ashr_i32 s4, s4, 2
	s_andn2_b32 s4, s4, 63
	s_ashr_i32 s5, s4, 31
	s_lshl_b64 s[4:5], s[4:5], 1
	s_add_u32 s12, s12, s4
	s_addc_u32 s13, s13, s5
	s_add_u32 s3, s45, s3
	s_addc_u32 s33, s46, 0
	v_mov_b32_e32 v58, v0
	s_add_u32 s38, s3, s4
	s_addc_u32 s39, s33, s5
	v_readfirstlane_b32 s3, v58
	s_ashr_i32 s33, s3, 6
	s_lshl_b32 s4, s33, 5
	s_ashr_i32 s5, s4, 31
	v_and_b32_e32 v1, 63, v58
	s_lshl_b64 s[4:5], s[4:5], 11
	s_add_u32 s36, s36, s4
	v_lshlrev_b32_e32 v206, 8, v1
	s_addc_u32 s37, s37, s5
	v_lshl_add_u64 v[18:19], s[12:13], 0, v[206:207]
	s_lshl_b32 s12, s33, 3
	s_and_b32 s4, s3, 0x3fffffc0
	s_ashr_i32 s13, s12, 31
	s_ashr_i32 s3, s3, 3
	v_lshl_add_u64 v[210:211], s[12:13], 1, v[18:19]
	s_lshl_b32 s5, s33, 4
	v_bfe_u32 v18, v58, 2, 4
	s_and_b32 s12, s3, 0xffffffe0
	v_and_or_b32 v18, s5, 48, v18
	s_ashr_i32 s13, s12, 31
	s_lshl_b32 s50, s33, 10
	v_lshlrev_b32_e32 v206, 8, v18
	v_lshlrev_b32_e32 v212, 3, v58
	s_cmp_lg_u32 0, -1
	v_lshl_add_u64 v[18:19], s[38:39], 0, v[206:207]
	v_and_b32_e32 v215, 24, v212
	s_cselect_b32 s3, 0, 0
	v_bfe_u32 v214, v58, 5, 1
	v_lshl_add_u64 v[18:19], s[12:13], 1, v[18:19]
	v_lshlrev_b32_e32 v206, 1, v215
	s_add_i32 s53, s50, s3
	s_mov_b32 s3, m0
	s_mov_b32 m0, s53
	s_nop 0
	global_load_lds_dwordx4 v[210:211], off
	s_mov_b32 m0, s3
	v_and_b32_e32 v213, 31, v58
	v_lshl_add_u64 v[208:209], v[18:19], 0, v[206:207]
	s_add_i32 s51, s53, 0x6000
	s_mov_b32 s3, m0
	s_mov_b32 m0, s51
	s_nop 0
	global_load_lds_dwordx4 v[208:209], off
	s_mov_b32 m0, s3
	v_lshl_add_u64 v[18:19], v[210:211], 0, s[0:1]
	v_lshlrev_b32_e32 v221, 4, v214
	s_add_i32 s3, s53, 0x2000
	s_mov_b32 s5, m0
	s_mov_b32 m0, s3
	s_nop 0
	global_load_lds_dwordx4 v[18:19], off
	s_mov_b32 m0, s5
	v_lshl_or_b32 v18, v213, 11, v221
	global_load_dwordx4 v[170:173], v18, s[36:37]
	global_load_dwordx4 v[162:165], v18, s[36:37] offset:32
	global_load_dwordx4 v[154:157], v18, s[36:37] offset:64
	global_load_dwordx4 v[146:149], v18, s[36:37] offset:96
	v_mov_b64_e32 v[32:33], v[16:17]
	v_mov_b64_e32 v[30:31], v[14:15]
	v_mov_b64_e32 v[28:29], v[12:13]
	v_mov_b64_e32 v[26:27], v[10:11]
	v_mov_b64_e32 v[24:25], v[8:9]
	v_mov_b64_e32 v[22:23], v[6:7]
	v_mov_b64_e32 v[20:21], v[4:5]
	v_mov_b64_e32 v[18:19], v[2:3]
	v_lshlrev_b32_e32 v34, 10, v214
	v_lshlrev_b32_e32 v35, 4, v213
	v_add3_u32 v220, 0, v34, v35
	v_lshl_add_u64 v[34:35], v[210:211], 0, s[6:7]
	s_add_i32 s3, s53, 0x4000
	s_mov_b32 s5, m0
	s_mov_b32 m0, s3
	s_nop 0
	global_load_lds_dwordx4 v[34:35], off
	s_mov_b32 m0, s5
	s_waitcnt vmcnt(3) lgkmcnt(0)
	s_barrier
	ds_read_b128 v[50:53], v220
	v_lshlrev_b32_e32 v59, 1, v58
	v_and_b32_e32 v216, 32, v59
	s_lshl_b32 s3, s4, 2
	s_add_i32 s52, s3, 0
	v_add_u32_e32 v98, 0, v216
	v_lshl_add_u32 v217, v213, 2, s52
	v_lshl_add_u64 v[202:203], v[208:209], 0, s[8:9]
	v_lshl_add_u64 v[204:205], v[210:211], 0, s[10:11]
	s_mov_b32 s54, -1
	v_mov_b32_e32 v198, 0
	s_mov_b32 s38, 0
	s_movk_i32 s12, 0x2000
	s_movk_i32 s55, 0x4000
	s_waitcnt vmcnt(3) lgkmcnt(0)
	v_mfma_f32_32x32x16_bf16 v[34:49], v[50:53], v[170:173], v[18:33]
	ds_read_b128 v[50:53], v220 offset:512
	s_waitcnt lgkmcnt(0)
	v_mfma_f32_32x32x16_bf16 v[18:33], v[50:53], v[170:173], v[18:33]
	ds_read_b128 v[50:53], v220 offset:2048
	s_waitcnt vmcnt(2) lgkmcnt(0)
	v_mfma_f32_32x32x16_bf16 v[34:49], v[50:53], v[162:165], v[34:49]
	ds_read_b128 v[50:53], v220 offset:2560
	s_waitcnt lgkmcnt(0)
	v_mfma_f32_32x32x16_bf16 v[18:33], v[50:53], v[162:165], v[18:33]
	ds_read_b128 v[50:53], v220 offset:4096
	s_waitcnt vmcnt(1) lgkmcnt(0)
	v_mfma_f32_32x32x16_bf16 v[34:49], v[50:53], v[154:157], v[34:49]
	ds_read_b128 v[50:53], v220 offset:4608
	s_waitcnt lgkmcnt(0)
	v_mfma_f32_32x32x16_bf16 v[18:33], v[50:53], v[154:157], v[18:33]
	ds_read_b128 v[50:53], v220 offset:6144
	ds_read_b128 v[54:57], v220 offset:6656
	s_waitcnt vmcnt(0) lgkmcnt(1)
	v_mfma_f32_32x32x16_bf16 v[34:49], v[50:53], v[146:149], v[34:49]
	v_lshlrev_b32_e32 v50, 4, v58
	v_and_b32_e32 v50, 0xc0, v50
	v_lshl_or_b32 v206, v214, 8, v50
	v_add3_u32 v219, v98, v215, v206
	s_waitcnt lgkmcnt(0)
	v_mfma_f32_32x32x16_bf16 v[18:33], v[54:57], v[146:149], v[18:33]
	s_nop 15
	s_nop 7
	s_nop 0
	v_max3_f32 v50, v34, v35, v18
	v_max3_f32 v51, v36, v37, v19
	s_nop 0
	v_max3_f32 v50, v50, v20, v21
	v_max3_f32 v51, v51, v40, v41
	s_nop 0
	v_max3_f32 v50, v50, v38, v39
	v_max3_f32 v51, v51, v24, v25
	s_nop 0
	v_max3_f32 v50, v50, v22, v23
	v_max3_f32 v51, v51, v44, v45
	s_nop 0
	v_max3_f32 v50, v50, v42, v43
	v_max3_f32 v51, v51, v28, v29
	s_nop 0
	v_max3_f32 v50, v50, v26, v27
	v_max3_f32 v51, v51, v48, v49
	s_nop 0
	v_max3_f32 v50, v50, v46, v47
	v_max3_f32 v51, v51, v32, v33
	s_nop 0
	v_max3_f32 v50, v50, v30, v31
	s_nop 0
	v_max_f32_e32 v50, v50, v51
	s_nop 0
	v_mov_b32_e32 v51, v50
	s_nop 1
	v_permlane32_swap_b32_e32 v50, v51
	v_max_f32_e32 v50, v50, v51
	s_nop 0
	v_add_f32_e32 v218, v207, v50
	v_sub_f32_e32 v34, v34, v50
	v_sub_f32_e32 v18, v18, v50
	v_sub_f32_e32 v35, v35, v50
	v_sub_f32_e32 v19, v19, v50
	v_sub_f32_e32 v36, v36, v50
	v_sub_f32_e32 v20, v20, v50
	v_sub_f32_e32 v37, v37, v50
	v_sub_f32_e32 v21, v21, v50
	v_sub_f32_e32 v38, v38, v50
	v_sub_f32_e32 v22, v22, v50
	v_sub_f32_e32 v39, v39, v50
	v_sub_f32_e32 v23, v23, v50
	v_sub_f32_e32 v40, v40, v50
	v_sub_f32_e32 v24, v24, v50
	v_sub_f32_e32 v41, v41, v50
	v_sub_f32_e32 v25, v25, v50
	v_sub_f32_e32 v42, v42, v50
	v_sub_f32_e32 v26, v26, v50
	v_sub_f32_e32 v43, v43, v50
	v_sub_f32_e32 v27, v27, v50
	v_sub_f32_e32 v44, v44, v50
	v_sub_f32_e32 v28, v28, v50
	v_sub_f32_e32 v45, v45, v50
	v_sub_f32_e32 v29, v29, v50
	v_sub_f32_e32 v46, v46, v50
	v_sub_f32_e32 v30, v30, v50
	v_sub_f32_e32 v47, v47, v50
	v_sub_f32_e32 v31, v31, v50
	v_sub_f32_e32 v48, v48, v50
	v_sub_f32_e32 v32, v32, v50
	v_sub_f32_e32 v49, v49, v50
	v_sub_f32_e32 v33, v33, v50
	s_nop 0
	v_xor_b32_e32 v50, 0x80000000, v218
	v_mov_b32_e32 v51, v50
	v_mov_b32_e32 v52, v50
	v_mov_b32_e32 v53, v50
	v_mov_b32_e32 v54, v50
	v_mov_b32_e32 v55, v50
	v_mov_b32_e32 v56, v50
	v_mov_b32_e32 v57, v50
	v_mov_b32_e32 v58, v50
	v_mov_b32_e32 v59, v50
	v_mov_b32_e32 v60, v50
	v_mov_b32_e32 v61, v50
	v_mov_b32_e32 v62, v50
	v_mov_b32_e32 v63, v50
	v_mov_b32_e32 v64, v50
	v_mov_b32_e32 v65, v50
	s_waitcnt vmcnt(0) lgkmcnt(0)
	s_barrier
	v_exp_f32_e32 v66, v18
	v_exp_f32_e32 v67, v19
	v_lshl_add_u64 v[18:19], v[210:211], 0, s[8:9]
	s_mov_b32 s3, m0
	s_mov_b32 m0, s53
	s_nop 0
	global_load_lds_dwordx4 v[18:19], off
	s_mov_b32 m0, s3
	v_lshl_add_u64 v[18:19], v[208:209], 0, s[0:1]
	s_add_i32 s3, s53, 0x8000
	s_mov_b32 s4, m0
	s_mov_b32 m0, s3
	s_nop 0
	global_load_lds_dwordx4 v[18:19], off
	s_mov_b32 m0, s4
	ds_read_b128 v[98:101], v220 offset:8192
	ds_read_b128 v[186:189], v220 offset:8704
	ds_read_b128 v[182:185], v220 offset:10240
	ds_read_b128 v[178:181], v220 offset:10752
	ds_read_b128 v[142:145], v220 offset:12288
	ds_read_b128 v[138:141], v220 offset:12800
	ds_read_b128 v[134:137], v220 offset:14336
	ds_read_b128 v[130:133], v220 offset:14848
	v_exp_f32_e32 v82, v34
	v_exp_f32_e32 v83, v35
	v_exp_f32_e32 v84, v36
	v_exp_f32_e32 v85, v37
	v_exp_f32_e32 v86, v38
	v_exp_f32_e32 v87, v39
	v_exp_f32_e32 v88, v40
	v_exp_f32_e32 v89, v41
	v_exp_f32_e32 v90, v42
	v_exp_f32_e32 v91, v43
	v_exp_f32_e32 v92, v44
	v_exp_f32_e32 v93, v45
	v_exp_f32_e32 v94, v46
	v_exp_f32_e32 v95, v47
	v_exp_f32_e32 v96, v48
	v_exp_f32_e32 v97, v49
	v_exp_f32_e32 v68, v20
	v_exp_f32_e32 v69, v21
	v_exp_f32_e32 v70, v22
	v_exp_f32_e32 v71, v23
	v_exp_f32_e32 v72, v24
	v_exp_f32_e32 v73, v25
	v_exp_f32_e32 v74, v26
	v_exp_f32_e32 v75, v27
	v_exp_f32_e32 v76, v28
	v_exp_f32_e32 v77, v29
	v_exp_f32_e32 v78, v30
	v_exp_f32_e32 v79, v31
	v_exp_f32_e32 v80, v32
	v_exp_f32_e32 v81, v33
	s_waitcnt vmcnt(2) lgkmcnt(0)
	s_barrier
	v_cmp_gt_u32_e64 s[4:5], 32, v1
	v_mov_b32_e32 v18, 0
	v_mov_b32_e32 v19, v207
	v_mov_b32_e32 v20, v207
	v_mov_b32_e32 v21, v207
	v_mov_b32_e32 v22, v207
	v_mov_b32_e32 v23, v207
	v_mov_b32_e32 v24, v207
	v_mov_b32_e32 v25, v207
	v_mov_b32_e32 v26, v207
	v_mov_b32_e32 v27, v207
	v_mov_b32_e32 v28, v207
	v_mov_b32_e32 v29, v207
	v_mov_b32_e32 v30, v207
	v_mov_b32_e32 v31, v207
	v_mov_b32_e32 v32, v207
	v_mov_b32_e32 v33, v207
	v_mov_b32_e32 v34, 0
	v_mov_b32_e32 v35, v207
	v_mov_b32_e32 v36, v207
	v_mov_b32_e32 v37, v207
	v_mov_b32_e32 v38, v207
	v_mov_b32_e32 v39, v207
	v_mov_b32_e32 v40, v207
	v_mov_b32_e32 v41, v207
	v_mov_b32_e32 v42, v207
	v_mov_b32_e32 v43, v207
	v_mov_b32_e32 v44, v207
	v_mov_b32_e32 v45, v207
	v_mov_b32_e32 v46, v207
	v_mov_b32_e32 v47, v207
	v_mov_b32_e32 v48, v207
	v_mov_b32_e32 v49, v207
	.p2alignl 6, 3212836864

.LBB0_1393:
	s_ashr_i32 s25, s24, 31
	s_lshl_b64 s[12:13], s[24:25], 19
	v_cmp_lt_i64_e32 vcc, s[26:27], v[150:151]
	s_add_u32 s26, s19, s12
	s_addc_u32 s27, s33, s13
	s_and_b64 s[12:13], vcc, exec
	s_cselect_b32 s25, s27, s43
	s_cselect_b32 s37, s26, s42
	s_ashr_i32 s23, s22, 31
	s_lshl_b64 s[12:13], s[22:23], 19
	s_add_u32 s28, s44, s12
	s_addc_u32 s29, s45, s13
	s_and_b64 s[12:13], vcc, exec
	s_cselect_b32 s23, s29, s41
	s_cselect_b32 s67, s28, s40
	s_add_u32 s30, s42, 0x40080
	s_addc_u32 s31, s43, 0
	s_add_u32 s68, s40, 0x100
	v_mov_b32_e32 v2, 0
	s_addc_u32 s69, s41, 0
	s_mov_b32 s12, -2
	s_waitcnt lgkmcnt(0)
	v_mov_b32_e32 v3, v2
	v_mov_b32_e32 v4, v2
	v_mov_b32_e32 v5, v2
	v_mov_b32_e32 v6, v2
	v_mov_b32_e32 v7, v2
	v_mov_b32_e32 v8, v2
	v_mov_b32_e32 v9, v2
	v_mov_b32_e32 v10, v2
	v_mov_b32_e32 v11, v2
	v_mov_b32_e32 v12, v2
	v_mov_b32_e32 v13, v2
	v_mov_b32_e32 v14, v2
	v_mov_b32_e32 v15, v2
	v_mov_b32_e32 v16, v2
	v_mov_b32_e32 v17, v2
	v_mov_b32_e32 v18, v2
	v_mov_b32_e32 v19, v2
	v_mov_b32_e32 v20, v2
	v_mov_b32_e32 v21, v2
	v_mov_b32_e32 v22, v2
	v_mov_b32_e32 v23, v2
	v_mov_b32_e32 v24, v2
	v_mov_b32_e32 v25, v2
	v_mov_b32_e32 v26, v2
	v_mov_b32_e32 v27, v2
	v_mov_b32_e32 v28, v2
	v_mov_b32_e32 v29, v2
	v_mov_b32_e32 v30, v2
	v_mov_b32_e32 v31, v2
	v_mov_b32_e32 v32, v2
	v_mov_b32_e32 v33, v2
	v_mov_b32_e32 v66, v2
	v_mov_b32_e32 v67, v2
	v_mov_b32_e32 v68, v2
	v_mov_b32_e32 v69, v2
	v_mov_b32_e32 v70, v2
	v_mov_b32_e32 v71, v2
	v_mov_b32_e32 v72, v2
	v_mov_b32_e32 v73, v2
	v_mov_b32_e32 v74, v2
	v_mov_b32_e32 v75, v2
	v_mov_b32_e32 v76, v2
	v_mov_b32_e32 v77, v2
	v_mov_b32_e32 v78, v2
	v_mov_b32_e32 v79, v2
	v_mov_b32_e32 v80, v2
	v_mov_b32_e32 v81, v2
	v_mov_b32_e32 v82, v2
	v_mov_b32_e32 v83, v2
	v_mov_b32_e32 v84, v2
	v_mov_b32_e32 v85, v2
	v_mov_b32_e32 v86, v2
	v_mov_b32_e32 v87, v2
	v_mov_b32_e32 v88, v2
	v_mov_b32_e32 v89, v2
	v_mov_b32_e32 v90, v2
	v_mov_b32_e32 v91, v2
	v_mov_b32_e32 v92, v2
	v_mov_b32_e32 v93, v2
	v_mov_b32_e32 v94, v2
	v_mov_b32_e32 v95, v2
	v_mov_b32_e32 v96, v2
	v_mov_b32_e32 v97, v2
	v_mov_b32_e32 v34, v2
	v_mov_b32_e32 v35, v2
	v_mov_b32_e32 v36, v2
	v_mov_b32_e32 v37, v2
	v_mov_b32_e32 v38, v2
	v_mov_b32_e32 v39, v2
	v_mov_b32_e32 v40, v2
	v_mov_b32_e32 v41, v2
	v_mov_b32_e32 v42, v2
	v_mov_b32_e32 v43, v2
	v_mov_b32_e32 v44, v2
	v_mov_b32_e32 v45, v2
	v_mov_b32_e32 v46, v2
	v_mov_b32_e32 v47, v2
	v_mov_b32_e32 v48, v2
	v_mov_b32_e32 v49, v2
	v_mov_b32_e32 v50, v2
	v_mov_b32_e32 v51, v2
	v_mov_b32_e32 v52, v2
	v_mov_b32_e32 v53, v2
	v_mov_b32_e32 v54, v2
	v_mov_b32_e32 v55, v2
	v_mov_b32_e32 v56, v2
	v_mov_b32_e32 v57, v2
	v_mov_b32_e32 v58, v2
	v_mov_b32_e32 v59, v2
	v_mov_b32_e32 v60, v2
	v_mov_b32_e32 v61, v2
	v_mov_b32_e32 v62, v2
	v_mov_b32_e32 v63, v2
	v_mov_b32_e32 v64, v2
	v_mov_b32_e32 v65, v2
	v_mov_b32_e32 v98, v2
	v_mov_b32_e32 v99, v2
	v_mov_b32_e32 v100, v2
	v_mov_b32_e32 v101, v2
	v_mov_b32_e32 v102, v2
	v_mov_b32_e32 v103, v2
	v_mov_b32_e32 v104, v2
	v_mov_b32_e32 v105, v2
	v_mov_b32_e32 v106, v2
	v_mov_b32_e32 v107, v2
	v_mov_b32_e32 v108, v2
	v_mov_b32_e32 v109, v2
	v_mov_b32_e32 v110, v2
	v_mov_b32_e32 v111, v2
	v_mov_b32_e32 v112, v2
	v_mov_b32_e32 v113, v2
	v_mov_b32_e32 v114, v2
	v_mov_b32_e32 v115, v2
	v_mov_b32_e32 v116, v2
	v_mov_b32_e32 v117, v2
	v_mov_b32_e32 v118, v2
	v_mov_b32_e32 v119, v2
	v_mov_b32_e32 v120, v2
	v_mov_b32_e32 v121, v2
	v_mov_b32_e32 v122, v2
	v_mov_b32_e32 v123, v2
	v_mov_b32_e32 v124, v2
	v_mov_b32_e32 v125, v2
	v_mov_b32_e32 v126, v2
	v_mov_b32_e32 v127, v2
	v_mov_b32_e32 v128, v2
	v_mov_b32_e32 v129, v2
	.p2alignl 6, 3212836864

.LBB0_1478:
	s_ashr_i32 s31, s30, 31
	s_lshl_b64 s[12:13], s[30:31], 19
	s_add_u32 s36, s3, s12
	s_addc_u32 s37, s19, s13
	s_and_b64 s[12:13], s[4:5], exec
	s_cselect_b32 s31, s37, s1
	s_cselect_b32 s43, s36, s0
	s_ashr_i32 s29, s28, 31
	s_lshl_b64 s[12:13], s[28:29], 19
	s_add_u32 s38, s33, s12
	s_addc_u32 s39, s48, s13
	s_and_b64 s[12:13], s[4:5], exec
	s_cselect_b32 s29, s39, s45
	s_cselect_b32 s67, s38, s44
	s_add_u32 s0, s0, 0x40080
	s_addc_u32 s1, s1, 0
	s_add_u32 s68, s44, 0x100
	v_mov_b32_e32 v2, 0
	s_addc_u32 s69, s45, 0
	s_mov_b32 s12, -2
	v_mov_b32_e32 v3, v2
	v_mov_b32_e32 v4, v2
	v_mov_b32_e32 v5, v2
	v_mov_b32_e32 v6, v2
	v_mov_b32_e32 v7, v2
	v_mov_b32_e32 v8, v2
	v_mov_b32_e32 v9, v2
	v_mov_b32_e32 v18, v2
	v_mov_b32_e32 v19, v2
	v_mov_b32_e32 v20, v2
	v_mov_b32_e32 v21, v2
	v_mov_b32_e32 v22, v2
	v_mov_b32_e32 v23, v2
	v_mov_b32_e32 v24, v2
	v_mov_b32_e32 v25, v2
	v_mov_b32_e32 v34, v2
	v_mov_b32_e32 v35, v2
	v_mov_b32_e32 v36, v2
	v_mov_b32_e32 v37, v2
	v_mov_b32_e32 v38, v2
	v_mov_b32_e32 v39, v2
	v_mov_b32_e32 v40, v2
	v_mov_b32_e32 v41, v2
	v_mov_b32_e32 v50, v2
	v_mov_b32_e32 v51, v2
	v_mov_b32_e32 v52, v2
	v_mov_b32_e32 v53, v2
	v_mov_b32_e32 v54, v2
	v_mov_b32_e32 v55, v2
	v_mov_b32_e32 v56, v2
	v_mov_b32_e32 v57, v2
	v_mov_b32_e32 v10, v2
	v_mov_b32_e32 v11, v2
	v_mov_b32_e32 v12, v2
	v_mov_b32_e32 v13, v2
	v_mov_b32_e32 v14, v2
	v_mov_b32_e32 v15, v2
	v_mov_b32_e32 v16, v2
	v_mov_b32_e32 v17, v2
	v_mov_b32_e32 v26, v2
	v_mov_b32_e32 v27, v2
	v_mov_b32_e32 v28, v2
	v_mov_b32_e32 v29, v2
	v_mov_b32_e32 v30, v2
	v_mov_b32_e32 v31, v2
	v_mov_b32_e32 v32, v2
	v_mov_b32_e32 v33, v2
	v_mov_b32_e32 v42, v2
	v_mov_b32_e32 v43, v2
	v_mov_b32_e32 v44, v2
	v_mov_b32_e32 v45, v2
	v_mov_b32_e32 v46, v2
	v_mov_b32_e32 v47, v2
	v_mov_b32_e32 v48, v2
	v_mov_b32_e32 v49, v2
	v_mov_b32_e32 v58, v2
	v_mov_b32_e32 v59, v2
	v_mov_b32_e32 v60, v2
	v_mov_b32_e32 v61, v2
	v_mov_b32_e32 v62, v2
	v_mov_b32_e32 v63, v2
	v_mov_b32_e32 v64, v2
	v_mov_b32_e32 v65, v2
	v_mov_b32_e32 v66, v2
	v_mov_b32_e32 v67, v2
	v_mov_b32_e32 v68, v2
	v_mov_b32_e32 v69, v2
	v_mov_b32_e32 v70, v2
	v_mov_b32_e32 v71, v2
	v_mov_b32_e32 v72, v2
	v_mov_b32_e32 v73, v2
	v_mov_b32_e32 v82, v2
	v_mov_b32_e32 v83, v2
	v_mov_b32_e32 v84, v2
	v_mov_b32_e32 v85, v2
	v_mov_b32_e32 v86, v2
	v_mov_b32_e32 v87, v2
	v_mov_b32_e32 v88, v2
	v_mov_b32_e32 v89, v2
	v_mov_b32_e32 v114, v2
	v_mov_b32_e32 v115, v2
	v_mov_b32_e32 v116, v2
	v_mov_b32_e32 v117, v2
	v_mov_b32_e32 v118, v2
	v_mov_b32_e32 v119, v2
	v_mov_b32_e32 v120, v2
	v_mov_b32_e32 v121, v2
	v_mov_b32_e32 v130, v2
	v_mov_b32_e32 v131, v2
	v_mov_b32_e32 v132, v2
	v_mov_b32_e32 v133, v2
	v_mov_b32_e32 v134, v2
	v_mov_b32_e32 v135, v2
	v_mov_b32_e32 v136, v2
	v_mov_b32_e32 v137, v2
	v_mov_b32_e32 v74, v2
	v_mov_b32_e32 v75, v2
	v_mov_b32_e32 v76, v2
	v_mov_b32_e32 v77, v2
	v_mov_b32_e32 v78, v2
	v_mov_b32_e32 v79, v2
	v_mov_b32_e32 v80, v2
	v_mov_b32_e32 v81, v2
	v_mov_b32_e32 v90, v2
	v_mov_b32_e32 v91, v2
	v_mov_b32_e32 v92, v2
	v_mov_b32_e32 v93, v2
	v_mov_b32_e32 v94, v2
	v_mov_b32_e32 v95, v2
	v_mov_b32_e32 v96, v2
	v_mov_b32_e32 v97, v2
	v_mov_b32_e32 v122, v2
	v_mov_b32_e32 v123, v2
	v_mov_b32_e32 v124, v2
	v_mov_b32_e32 v125, v2
	v_mov_b32_e32 v126, v2
	v_mov_b32_e32 v127, v2
	v_mov_b32_e32 v128, v2
	v_mov_b32_e32 v129, v2
	v_mov_b32_e32 v138, v2
	v_mov_b32_e32 v139, v2
	v_mov_b32_e32 v140, v2
	v_mov_b32_e32 v141, v2
	v_mov_b32_e32 v142, v2
	v_mov_b32_e32 v143, v2
	v_mov_b32_e32 v144, v2
	v_mov_b32_e32 v145, v2
	.p2alignl 6, 3212836864

.LBB0_1560:
	s_add_u32 s27, s30, 0x100
	v_mov_b32_e32 v2, 0
	s_addc_u32 s67, s31, 0
	s_mov_b32 s12, -2
	s_waitcnt lgkmcnt(0)
	v_mov_b32_e32 v3, v2
	v_mov_b32_e32 v4, v2
	v_mov_b32_e32 v5, v2
	v_mov_b32_e32 v6, v2
	v_mov_b32_e32 v7, v2
	v_mov_b32_e32 v8, v2
	v_mov_b32_e32 v9, v2
	v_mov_b32_e32 v10, v2
	v_mov_b32_e32 v11, v2
	v_mov_b32_e32 v12, v2
	v_mov_b32_e32 v13, v2
	v_mov_b32_e32 v14, v2
	v_mov_b32_e32 v15, v2
	v_mov_b32_e32 v16, v2
	v_mov_b32_e32 v17, v2
	v_mov_b32_e32 v18, v2
	v_mov_b32_e32 v19, v2
	v_mov_b32_e32 v20, v2
	v_mov_b32_e32 v21, v2
	v_mov_b32_e32 v22, v2
	v_mov_b32_e32 v23, v2
	v_mov_b32_e32 v24, v2
	v_mov_b32_e32 v25, v2
	v_mov_b32_e32 v26, v2
	v_mov_b32_e32 v27, v2
	v_mov_b32_e32 v28, v2
	v_mov_b32_e32 v29, v2
	v_mov_b32_e32 v30, v2
	v_mov_b32_e32 v31, v2
	v_mov_b32_e32 v32, v2
	v_mov_b32_e32 v33, v2
	v_mov_b32_e32 v66, v2
	v_mov_b32_e32 v67, v2
	v_mov_b32_e32 v68, v2
	v_mov_b32_e32 v69, v2
	v_mov_b32_e32 v70, v2
	v_mov_b32_e32 v71, v2
	v_mov_b32_e32 v72, v2
	v_mov_b32_e32 v73, v2
	v_mov_b32_e32 v74, v2
	v_mov_b32_e32 v75, v2
	v_mov_b32_e32 v76, v2
	v_mov_b32_e32 v77, v2
	v_mov_b32_e32 v78, v2
	v_mov_b32_e32 v79, v2
	v_mov_b32_e32 v80, v2
	v_mov_b32_e32 v81, v2
	v_mov_b32_e32 v82, v2
	v_mov_b32_e32 v83, v2
	v_mov_b32_e32 v84, v2
	v_mov_b32_e32 v85, v2
	v_mov_b32_e32 v86, v2
	v_mov_b32_e32 v87, v2
	v_mov_b32_e32 v88, v2
	v_mov_b32_e32 v89, v2
	v_mov_b32_e32 v90, v2
	v_mov_b32_e32 v91, v2
	v_mov_b32_e32 v92, v2
	v_mov_b32_e32 v93, v2
	v_mov_b32_e32 v94, v2
	v_mov_b32_e32 v95, v2
	v_mov_b32_e32 v96, v2
	v_mov_b32_e32 v97, v2
	v_mov_b32_e32 v34, v2
	v_mov_b32_e32 v35, v2
	v_mov_b32_e32 v36, v2
	v_mov_b32_e32 v37, v2
	v_mov_b32_e32 v38, v2
	v_mov_b32_e32 v39, v2
	v_mov_b32_e32 v40, v2
	v_mov_b32_e32 v41, v2
	v_mov_b32_e32 v42, v2
	v_mov_b32_e32 v43, v2
	v_mov_b32_e32 v44, v2
	v_mov_b32_e32 v45, v2
	v_mov_b32_e32 v46, v2
	v_mov_b32_e32 v47, v2
	v_mov_b32_e32 v48, v2
	v_mov_b32_e32 v49, v2
	v_mov_b32_e32 v50, v2
	v_mov_b32_e32 v51, v2
	v_mov_b32_e32 v52, v2
	v_mov_b32_e32 v53, v2
	v_mov_b32_e32 v54, v2
	v_mov_b32_e32 v55, v2
	v_mov_b32_e32 v56, v2
	v_mov_b32_e32 v57, v2
	v_mov_b32_e32 v58, v2
	v_mov_b32_e32 v59, v2
	v_mov_b32_e32 v60, v2
	v_mov_b32_e32 v61, v2
	v_mov_b32_e32 v62, v2
	v_mov_b32_e32 v63, v2
	v_mov_b32_e32 v64, v2
	v_mov_b32_e32 v65, v2
	v_mov_b32_e32 v98, v2
	v_mov_b32_e32 v99, v2
	v_mov_b32_e32 v100, v2
	v_mov_b32_e32 v101, v2
	v_mov_b32_e32 v102, v2
	v_mov_b32_e32 v103, v2
	v_mov_b32_e32 v104, v2
	v_mov_b32_e32 v105, v2
	v_mov_b32_e32 v106, v2
	v_mov_b32_e32 v107, v2
	v_mov_b32_e32 v108, v2
	v_mov_b32_e32 v109, v2
	v_mov_b32_e32 v110, v2
	v_mov_b32_e32 v111, v2
	v_mov_b32_e32 v112, v2
	v_mov_b32_e32 v113, v2
	v_mov_b32_e32 v114, v2
	v_mov_b32_e32 v115, v2
	v_mov_b32_e32 v116, v2
	v_mov_b32_e32 v117, v2
	v_mov_b32_e32 v118, v2
	v_mov_b32_e32 v119, v2
	v_mov_b32_e32 v120, v2
	v_mov_b32_e32 v121, v2
	v_mov_b32_e32 v122, v2
	v_mov_b32_e32 v123, v2
	v_mov_b32_e32 v124, v2
	v_mov_b32_e32 v125, v2
	v_mov_b32_e32 v126, v2
	v_mov_b32_e32 v127, v2
	v_mov_b32_e32 v128, v2
	v_mov_b32_e32 v129, v2
	.p2alignl 6, 3212836864

.LBB0_1605:
	s_add_u32 s9, s48, 0x100
	v_mov_b32_e32 v42, 0
	s_addc_u32 s77, s49, 0
	s_mov_b32 s12, -2
	v_mov_b32_e32 v43, v42
	v_mov_b32_e32 v44, v42
	v_mov_b32_e32 v45, v42
	v_mov_b32_e32 v46, v42
	v_mov_b32_e32 v47, v42
	v_mov_b32_e32 v48, v42
	v_mov_b32_e32 v49, v42
	v_mov_b32_e32 v2, v42
	v_mov_b32_e32 v3, v42
	v_mov_b32_e32 v4, v42
	v_mov_b32_e32 v5, v42
	v_mov_b32_e32 v6, v42
	v_mov_b32_e32 v7, v42
	v_mov_b32_e32 v8, v42
	v_mov_b32_e32 v9, v42
	v_mov_b32_e32 v66, v42
	v_mov_b32_e32 v67, v42
	v_mov_b32_e32 v68, v42
	v_mov_b32_e32 v69, v42
	v_mov_b32_e32 v78, v42
	v_mov_b32_e32 v79, v42
	v_mov_b32_e32 v80, v42
	v_mov_b32_e32 v81, v42
	v_mov_b32_e32 v18, v42
	v_mov_b32_e32 v19, v42
	v_mov_b32_e32 v20, v42
	v_mov_b32_e32 v21, v42
	v_mov_b32_e32 v22, v42
	v_mov_b32_e32 v23, v42
	v_mov_b32_e32 v24, v42
	v_mov_b32_e32 v25, v42
	v_mov_b32_e32 v98, v42
	v_mov_b32_e32 v99, v42
	v_mov_b32_e32 v100, v42
	v_mov_b32_e32 v101, v42
	v_mov_b32_e32 v102, v42
	v_mov_b32_e32 v103, v42
	v_mov_b32_e32 v104, v42
	v_mov_b32_e32 v105, v42
	v_mov_b32_e32 v10, v42
	v_mov_b32_e32 v11, v42
	v_mov_b32_e32 v12, v42
	v_mov_b32_e32 v13, v42
	v_mov_b32_e32 v14, v42
	v_mov_b32_e32 v15, v42
	v_mov_b32_e32 v16, v42
	v_mov_b32_e32 v17, v42
	v_mov_b32_e32 v114, v42
	v_mov_b32_e32 v115, v42
	v_mov_b32_e32 v116, v42
	v_mov_b32_e32 v117, v42
	v_mov_b32_e32 v118, v42
	v_mov_b32_e32 v119, v42
	v_mov_b32_e32 v120, v42
	v_mov_b32_e32 v121, v42
	v_mov_b32_e32 v26, v42
	v_mov_b32_e32 v27, v42
	v_mov_b32_e32 v28, v42
	v_mov_b32_e32 v29, v42
	v_mov_b32_e32 v30, v42
	v_mov_b32_e32 v31, v42
	v_mov_b32_e32 v32, v42
	v_mov_b32_e32 v33, v42
	v_mov_b32_e32 v82, v42
	v_mov_b32_e32 v83, v42
	v_mov_b32_e32 v84, v42
	v_mov_b32_e32 v85, v42
	v_mov_b32_e32 v86, v42
	v_mov_b32_e32 v87, v42
	v_mov_b32_e32 v88, v42
	v_mov_b32_e32 v89, v42
	v_mov_b32_e32 v34, v42
	v_mov_b32_e32 v35, v42
	v_mov_b32_e32 v36, v42
	v_mov_b32_e32 v37, v42
	v_mov_b32_e32 v38, v42
	v_mov_b32_e32 v39, v42
	v_mov_b32_e32 v40, v42
	v_mov_b32_e32 v41, v42
	v_mov_b32_e32 v90, v42
	v_mov_b32_e32 v91, v42
	v_mov_b32_e32 v92, v42
	v_mov_b32_e32 v93, v42
	v_mov_b32_e32 v94, v42
	v_mov_b32_e32 v95, v42
	v_mov_b32_e32 v96, v42
	v_mov_b32_e32 v97, v42
	v_mov_b32_e32 v58, v42
	v_mov_b32_e32 v59, v42
	v_mov_b32_e32 v60, v42
	v_mov_b32_e32 v61, v42
	v_mov_b32_e32 v62, v42
	v_mov_b32_e32 v63, v42
	v_mov_b32_e32 v64, v42
	v_mov_b32_e32 v65, v42
	v_mov_b32_e32 v122, v42
	v_mov_b32_e32 v123, v42
	v_mov_b32_e32 v124, v42
	v_mov_b32_e32 v125, v42
	v_mov_b32_e32 v126, v42
	v_mov_b32_e32 v127, v42
	v_mov_b32_e32 v128, v42
	v_mov_b32_e32 v129, v42
	v_mov_b32_e32 v50, v42
	v_mov_b32_e32 v51, v42
	v_mov_b32_e32 v52, v42
	v_mov_b32_e32 v53, v42
	v_mov_b32_e32 v54, v42
	v_mov_b32_e32 v55, v42
	v_mov_b32_e32 v56, v42
	v_mov_b32_e32 v57, v42
	v_mov_b32_e32 v130, v42
	v_mov_b32_e32 v131, v42
	v_mov_b32_e32 v132, v42
	v_mov_b32_e32 v133, v42
	v_mov_b32_e32 v134, v42
	v_mov_b32_e32 v135, v42
	v_mov_b32_e32 v136, v42
	v_mov_b32_e32 v137, v42
	v_mov_b32_e32 v70, v42
	v_mov_b32_e32 v71, v42
	v_mov_b32_e32 v72, v42
	v_mov_b32_e32 v73, v42
	v_mov_b32_e32 v74, v42
	v_mov_b32_e32 v75, v42
	v_mov_b32_e32 v76, v42
	v_mov_b32_e32 v77, v42
	.p2alignl 6, 3212836864
